# v42 + attention loop: V-tile LDS-DMA issues behind MFMAs 5 and 9
# baseline (speedup 1.0000x reference)
; #define SB() __builtin_amdgcn_sched_barrier(0)
; #define MF32(a,b,c) __builtin_amdgcn_mfma_f32_32x32x16_bf16(a,b,c,0,0,0)
; #define EXP1(x) x=__builtin_amdgcn_exp2f((x)-mh_)
; __device__ __forceinline__ bf16x8 vfrag(lds_cptr vp,int i){ const s16x4 lo=vtr(vp+(i&3)*4096+(i>>2)*1024), hh=vtr(vp+(i&3)*4096+(i>>2)*1024+512); return (bf16x8){lo[0],lo[1],lo[2],lo[3],hh[0],hh[1],hh[2],hh[3]}; }
; __device__ __forceinline__ u32x4 packw(const f32x16&p,int base){ u32x4 w; w[0]=cvtpk_s(p[base],p[base+1]); w[1]=cvtpk_s(p[base+2],p[base+3]); w[2]=cvtpk_s(p[base+4],p[base+5]); w[3]=cvtpk_s(p[base+6],p[base+7]); return w; }
;   #define KF(i) LDSQ(kpn+((i)>>1)*2048+((i)&1)*512)
;   #define QF(d0) LDSQ(qp+(d0)*1024)
; template<int THRL,bool FIRST> __device__ __forceinline__ void step_main(f32x16&p0,f32x16&p1,f32x16&n0,f32x16&n1,St&S,lds_cptr kpn,lds_cptr qp,lds_cptr vp,float*wsf,int r32,int hi,float&rm){
;     ...
;   bf16x8 ka=KF(0),kb=KF(1),kc=KF(2),kd=KF(3),qa=QF(0),qb=QF(1);
;   decide<THRL,FIRST>(rm,S,wsf,r32,hi);
;   u32x4 pw0,pw1,pw2,pw3; const float mh_=S.mhat; const f32x16 z=f32x16{};
;   SB();
;   n0=MF32(ka,qa,z); ka=KF(4); EXP1(p0[0]);EXP1(p0[1]);EXP1(p0[2]); SB();
;   n1=MF32(kb,qa,z); kb=KF(5); qa=QF(2); EXP1(p0[3]);EXP1(p0[4]);EXP1(p0[5]); SB();
;   n0=MF32(kc,qb,n0);   kc=KF(6); EXP1(p0[6]);EXP1(p0[7]);EXP1(p0[8]); SB();
;   n1=MF32(kd,qb,n1);   kd=KF(7); qb=QF(3); EXP1(p0[9]);EXP1(p0[10]);EXP1(p0[11]); SB();
;   bf16x8 vfa=vfrag(vp,0);
;   n0=MF32(ka,qa,n0);   EXP1(p0[12]);EXP1(p0[13]);EXP1(p0[14]); pw0=packw(p0,0); SB();
;   bf16x8 vfb=vfrag(vp,1);
;   n1=MF32(kb,qa,n1);   EXP1(p0[15]);EXP1(p1[0]);EXP1(p1[1]); SB();
;   bf16x8 vfc=vfrag(vp,2);
;   n0=MF32(kc,qb,n0);   EXP1(p1[2]);EXP1(p1[3]);EXP1(p1[4]); pw1=packw(p0,8); SB();
;   bf16x8 vfd=vfrag(vp,3);
;   n1=MF32(kd,qb,n1);   EXP1(p1[5]);EXP1(p1[6]);EXP1(p1[7]); SB();
;     ...
;   float sa=p0[0]+p0[1];
;     ...
;   PVG(0,pw0,vfa,4, p0[2],p0[3],p0[4],p0[5],   do{EXP1(p1[8]);EXP1(p1[9]);}while(0));
;   PVG(1,pw0,vfb,5, p0[6],p0[7],p0[8],p0[9], do{EXP1(p1[10]);EXP1(p1[11]);}while(0));
;   PVG(2,pw0,vfc,6, p0[10],p0[11],p0[12],p0[13], do{EXP1(p1[12]);EXP1(p1[13]);}while(0));
;   PVG(3,pw0,vfd,7, p0[14],p0[15],p1[0],p1[1],   do{EXP1(p1[14]);EXP1(p1[15]);}while(0));
.LBB0_277:
	s_add_i32 s4, s91, 0x2000
	s_cmpk_lg_i32 s91, 0x4000
	s_cselect_b32 s88, s4, 0
	s_add_i32 s90, s90, 2
	v_mfma_f32_32x32x16_bf16 v[98:113], v[204:207], v[164:167], v[146:161]
	s_add_i32 s4, s88, s84
	s_add_u32 s60, s58, 0xc0000
	s_addc_u32 s61, s59, 0
	s_mov_b32 s5, m0
	s_mov_b32 m0, s4
	s_nop 0
	global_load_lds_dwordx4 v252, s[60:61]
	s_mov_b32 m0, s5
	v_exp_f32_e32 v130, v130
	v_exp_f32_e32 v131, v131
	v_exp_f32_e32 v132, v132
	v_exp_f32_e32 v133, v133
	v_exp_f32_e32 v134, v134
	v_exp_f32_e32 v135, v135
	v_mfma_f32_32x32x16_bf16 v[82:97], v[208:211], v[164:167], v[146:161]
	v_mfma_f32_32x32x16_bf16 v[98:113], v[212:215], v[168:171], v[98:113]
	v_exp_f32_e32 v136, v136
	v_exp_f32_e32 v137, v137
	v_exp_f32_e32 v138, v138
	v_mfma_f32_32x32x16_bf16 v[82:97], v[216:219], v[168:171], v[82:97]
	v_exp_f32_e32 v139, v139
	v_exp_f32_e32 v140, v140
	v_exp_f32_e32 v141, v141
	v_mfma_f32_32x32x16_bf16 v[98:113], v[220:223], v[172:175], v[98:113]
	s_add_u32 s60, s50, 0xc0000
	s_addc_u32 s61, s51, 0
	s_mov_b32 s4, m0
	s_mov_b32 m0, s80
	s_nop 0
	global_load_lds_dwordx4 v250, s[60:61]
	s_mov_b32 m0, s4
	v_exp_f32_e32 v142, v142
	ds_read_b64_tr_b16 v[4:5], v246 offset:40960
	ds_read_b64_tr_b16 v[6:7], v246 offset:41472
	v_exp_f32_e32 v143, v143
	v_exp_f32_e32 v144, v144
	v_cvt_pk_bf16_f32 v8, v130, v131
	v_cvt_pk_bf16_f32 v9, v132, v133
	v_cvt_pk_bf16_f32 v10, v134, v135
	v_cvt_pk_bf16_f32 v11, v136, v137
	v_mfma_f32_32x32x16_bf16 v[82:97], v[224:227], v[172:175], v[82:97]
	ds_read_b64_tr_b16 v[178:179], v246 offset:45056
	ds_read_b64_tr_b16 v[180:181], v246 offset:45568
	v_exp_f32_e32 v145, v145
	v_exp_f32_e32 v114, v114
	v_exp_f32_e32 v115, v115
	v_mfma_f32_32x32x16_bf16 v[98:113], v[228:231], v[236:239], v[98:113]
	ds_read_b64_tr_b16 v[182:183], v246 offset:49152
	ds_read_b64_tr_b16 v[184:185], v246 offset:49664
	v_exp_f32_e32 v116, v116
	v_exp_f32_e32 v117, v117
	v_exp_f32_e32 v118, v118
	v_cvt_pk_bf16_f32 v186, v138, v139
	v_cvt_pk_bf16_f32 v187, v140, v141
	v_cvt_pk_bf16_f32 v188, v142, v143
	v_cvt_pk_bf16_f32 v189, v144, v145
	v_mfma_f32_32x32x16_bf16 v[82:97], v[232:235], v[236:239], v[82:97]
	v_add_u32_e32 v240, s91, v249
	ds_read_b64_tr_b16 v[190:191], v246 offset:53248
	ds_read_b64_tr_b16 v[192:193], v246 offset:53760
	v_exp_f32_e32 v119, v119
	v_exp_f32_e32 v120, v120
	v_exp_f32_e32 v121, v121
	s_waitcnt lgkmcnt(6)
	v_mfma_f32_32x32x16_bf16 v[18:33], v[8:11], v[4:7], v[18:33]
	ds_read_b64_tr_b16 v[12:13], v246 offset:41984
	ds_read_b64_tr_b16 v[14:15], v246 offset:42496
	ds_read_b128 v[204:207], v240
	s_add_u32 s60, s50, 0xc0080
	s_addc_u32 s61, s51, 0
	s_mov_b32 s4, m0
	s_mov_b32 m0, s83
	s_nop 0
	global_load_lds_dwordx4 v250, s[60:61]
	s_mov_b32 m0, s4
	v_add_f32_e32 v194, v130, v131
	v_exp_f32_e32 v122, v122
	v_exp_f32_e32 v123, v123
	v_add_f32_e32 v194, v132, v194
	v_add_f32_e32 v4, v133, v194
	v_add_f32_e32 v4, v134, v4
	v_add_f32_e32 v194, v135, v4
	s_waitcnt lgkmcnt(7)
	v_mfma_f32_32x32x16_bf16 v[34:49], v[8:11], v[178:181], v[34:49]
	ds_read_b64_tr_b16 v[4:5], v246 offset:46080
	ds_read_b64_tr_b16 v[6:7], v246 offset:46592
	ds_read_b128 v[208:211], v240 offset:512
	v_exp_f32_e32 v124, v124
	v_exp_f32_e32 v125, v125
	v_add_f32_e32 v194, v136, v194
	v_add_f32_e32 v178, v137, v194
	v_add_f32_e32 v178, v138, v178
	v_add_f32_e32 v194, v139, v178
	s_waitcnt lgkmcnt(8)
	v_mfma_f32_32x32x16_bf16 v[50:65], v[8:11], v[182:185], v[50:65]
	ds_read_b64_tr_b16 v[178:179], v246 offset:50176
	ds_read_b64_tr_b16 v[180:181], v246 offset:50688
	ds_read_b128 v[212:215], v240 offset:2048
	v_exp_f32_e32 v126, v126
	v_exp_f32_e32 v127, v127
	v_add_f32_e32 v194, v140, v194
	v_add_f32_e32 v182, v141, v194
	v_add_f32_e32 v182, v142, v182
	v_add_f32_e32 v194, v143, v182
	s_waitcnt lgkmcnt(9)
; #define EXP1(x) x=__builtin_amdgcn_exp2f((x)-mh_)
; template<int THRL,bool FIRST> __device__ __forceinline__ void step_main(f32x16&p0,f32x16&p1,f32x16&n0,f32x16&n1,St&S,lds_cptr kpn,lds_cptr qp,lds_cptr vp,float*wsf,int r32,int hi,float&rm){
;     ...
;   PVG(0,pw0,vfa,4, p0[2],p0[3],p0[4],p0[5],   do{EXP1(p1[8]);EXP1(p1[9]);}while(0));
;   PVG(1,pw0,vfb,5, p0[6],p0[7],p0[8],p0[9], do{EXP1(p1[10]);EXP1(p1[11]);}while(0));
;   PVG(2,pw0,vfc,6, p0[10],p0[11],p0[12],p0[13], do{EXP1(p1[12]);EXP1(p1[13]);}while(0));
;   PVG(3,pw0,vfd,7, p0[14],p0[15],p1[0],p1[1],   do{EXP1(p1[14]);EXP1(p1[15]);}while(0));
;   PVG(4,pw1,vfa,8, p1[2],p1[3],p1[4],p1[5],   pw2=packw(p1,0));
;   PVG(5,pw1,vfb,9, p1[6],p1[7],p1[8],p1[9], pw3=packw(p1,8));
;   PVG(6,pw1,vfc,10, p1[10],p1[11],p1[12],p1[13], do{}while(0));
;   PVG(7,pw1,vfd,11, p1[14],p1[15],0.f,0.f, do{}while(0));
;   float ma,mb;
;     ...
;   PVG(8,pw2,vfa,12,0.f,0.f,0.f,0.f, do{ma=max3f(n0[0],n0[1],n1[0]);mb=max3f(n0[2],n0[3],n1[1]);PINAB();}while(0));
;   PVG(9,pw2,vfb,13,0.f,0.f,0.f,0.f, do{ma=max3f(ma,n1[2],n1[3]);mb=max3f(mb,n0[4],n0[5]);PINAB();}while(0));
;   PVG(10,pw2,vfc,14,0.f,0.f,0.f,0.f, do{ma=max3f(ma,n0[6],n0[7]);mb=max3f(mb,n1[4],n1[5]);PINAB();}while(0));
;   PVG(11,pw2,vfd,15,0.f,0.f,0.f,0.f, do{ma=max3f(ma,n1[6],n1[7]);mb=max3f(mb,n0[8],n0[9]);PINAB();}while(0));
;   PVG(12,pw3,vfa,16,0.f,0.f,0.f,0.f, do{ma=max3f(ma,n0[10],n0[11]);mb=max3f(mb,n1[8],n1[9]);PINAB();}while(0));
;   PVG(13,pw3,vfb,16,0.f,0.f,0.f,0.f, do{ma=max3f(ma,n1[10],n1[11]);mb=max3f(mb,n0[12],n0[13]);PINAB();}while(0));
;   PVG(14,pw3,vfc,16,0.f,0.f,0.f,0.f, do{ma=max3f(ma,n0[14],n0[15]);mb=max3f(mb,n1[12],n1[13]);PINAB();}while(0));
;   PVG(15,pw3,vfd,16,0.f,0.f,0.f,0.f, do{ma=max3f(ma,n1[14],n1[15]);ma=max2f(ma,mb);PINAB();}while(0));
;     ...
;   { auto rr=__builtin_amdgcn_permlane32_swap(__float_as_uint(ma),__float_as_uint(ma),false,false); rm=max2f(__uint_as_float(rr[0]),__uint_as_float(rr[1])); }
;     ...
;   S.l_reg+=sa;
; template<int THRL> __device__ __forceinline__ void unit(int qb,const bf16*Q,const bf16*K,const bf16*V,bf16*O,char*shm){
;     ...
;     for(t=2;t<NT-4;t+=2){
;       DMA_K(t+2,ks2); DMA_V(t+1,VBUF);
;       step_main<THRL,false>(pA0,pA1,pB0,pB1,S,kp0+ks1,qp,vp0,wsf,r32,hi,rm); A128_WAITBAR(); ROT();
;       DMA_K(t+3,ks2); DMA_V(t+2,0);
;       step_main<THRL,false>(pB0,pB1,pA0,pA1,S,kp0+ks1,qp,vp0+VBUF,wsf,r32,hi,rm); A128_WAITBAR(); ROT();
;     }
	v_mfma_f32_32x32x16_bf16 v[66:81], v[8:11], v[190:193], v[66:81]
	ds_read_b64_tr_b16 v[182:183], v246 offset:54272
	ds_read_b64_tr_b16 v[184:185], v246 offset:54784
	ds_read_b128 v[216:219], v240 offset:2560
	v_exp_f32_e32 v128, v128
	v_exp_f32_e32 v129, v129
	v_add_f32_e32 v194, v144, v194
	v_add_f32_e32 v8, v145, v194
	v_add_f32_e32 v8, v114, v8
	v_add_f32_e32 v190, v115, v8
	s_waitcnt lgkmcnt(10)
	v_mfma_f32_32x32x16_bf16 v[18:33], v[186:189], v[12:15], v[18:33]
	ds_read_b64_tr_b16 v[8:9], v246 offset:43008
	ds_read_b64_tr_b16 v[10:11], v246 offset:43520
	ds_read_b128 v[220:223], v240 offset:4096
	v_add_f32_e32 v190, v116, v190
	v_add_f32_e32 v190, v117, v190
	v_add_f32_e32 v190, v118, v190
	v_add_f32_e32 v194, v119, v190
	v_cvt_pk_bf16_f32 v12, v114, v115
	v_cvt_pk_bf16_f32 v13, v116, v117
	v_cvt_pk_bf16_f32 v14, v118, v119
	v_cvt_pk_bf16_f32 v15, v120, v121
	s_waitcnt lgkmcnt(10)
	v_mfma_f32_32x32x16_bf16 v[34:49], v[186:189], v[4:7], v[34:49]
	ds_read_b64_tr_b16 v[190:191], v246 offset:47104
	ds_read_b64_tr_b16 v[192:193], v246 offset:47616
	ds_read_b128 v[224:227], v240 offset:4608
	v_add_f32_e32 v194, v120, v194
	v_add_f32_e32 v194, v121, v194
	v_add_f32_e32 v194, v122, v194
	v_add_f32_e32 v198, v123, v194
	v_cvt_pk_bf16_f32 v4, v122, v123
	v_cvt_pk_bf16_f32 v5, v124, v125
	v_cvt_pk_bf16_f32 v6, v126, v127
	v_cvt_pk_bf16_f32 v7, v128, v129
	s_waitcnt lgkmcnt(10)
	v_mfma_f32_32x32x16_bf16 v[50:65], v[186:189], v[178:181], v[50:65]
	ds_read_b64_tr_b16 v[194:195], v246 offset:51200
	ds_read_b64_tr_b16 v[196:197], v246 offset:51712
	ds_read_b128 v[228:231], v240 offset:6144
	v_add_f32_e32 v198, v124, v198
	v_add_f32_e32 v198, v125, v198
	v_add_f32_e32 v198, v126, v198
	v_add_f32_e32 v198, v127, v198
	s_waitcnt lgkmcnt(10)
	v_mfma_f32_32x32x16_bf16 v[66:81], v[186:189], v[182:185], v[66:81]
	ds_read_b64_tr_b16 v[178:179], v246 offset:55296
	ds_read_b64_tr_b16 v[180:181], v246 offset:55808
	ds_read_b128 v[232:235], v240 offset:6656
	v_add_f32_e32 v198, v128, v198
	v_add_f32_e32 v198, v129, v198
	v_add_f32_e32 v198, 0, v198
	s_waitcnt lgkmcnt(10)
	v_mfma_f32_32x32x16_bf16 v[18:33], v[12:15], v[8:11], v[18:33]
	ds_read_b64_tr_b16 v[182:183], v246 offset:44032
	ds_read_b64_tr_b16 v[184:185], v246 offset:44544
	v_max3_f32 v186, v98, v99, v82
	v_max3_f32 v187, v100, v101, v83
	s_nop 0
	s_waitcnt lgkmcnt(9)
	v_mfma_f32_32x32x16_bf16 v[34:49], v[12:15], v[190:193], v[34:49]
	ds_read_b64_tr_b16 v[8:9], v246 offset:48128
	ds_read_b64_tr_b16 v[10:11], v246 offset:48640
	v_max3_f32 v199, v186, v84, v85
	v_max3_f32 v200, v187, v102, v103
	s_nop 0
	s_waitcnt lgkmcnt(8)
	v_mfma_f32_32x32x16_bf16 v[50:65], v[12:15], v[194:197], v[50:65]
	ds_read_b64_tr_b16 v[186:187], v246 offset:52224
	ds_read_b64_tr_b16 v[188:189], v246 offset:52736
	v_max3_f32 v199, v199, v104, v105
	v_max3_f32 v200, v200, v86, v87
	s_nop 0
	s_waitcnt lgkmcnt(7)
	v_mfma_f32_32x32x16_bf16 v[66:81], v[12:15], v[178:181], v[66:81]
	ds_read_b64_tr_b16 v[190:191], v246 offset:56320
	ds_read_b64_tr_b16 v[192:193], v246 offset:56832
	v_max3_f32 v194, v199, v88, v89
	v_max3_f32 v195, v200, v106, v107
	s_nop 0
	s_waitcnt lgkmcnt(6)
	v_mfma_f32_32x32x16_bf16 v[18:33], v[4:7], v[182:185], v[18:33]
	v_max3_f32 v12, v194, v108, v109
	v_max3_f32 v13, v195, v90, v91
	s_nop 0
	s_waitcnt lgkmcnt(4)
	v_mfma_f32_32x32x16_bf16 v[34:49], v[4:7], v[8:11], v[34:49]
	v_max3_f32 v12, v12, v92, v93
	v_max3_f32 v13, v13, v110, v111
	s_nop 0
	s_waitcnt lgkmcnt(2)
	v_mfma_f32_32x32x16_bf16 v[50:65], v[4:7], v[186:189], v[50:65]
	v_max3_f32 v8, v12, v112, v113
	v_max3_f32 v9, v13, v94, v95
	s_nop 0
	s_waitcnt lgkmcnt(0)
	v_mfma_f32_32x32x16_bf16 v[66:81], v[4:7], v[190:193], v[66:81]
	v_max3_f32 v8, v8, v96, v97
	s_nop 0
	v_max_f32_e32 v8, v8, v9
	s_nop 0
	s_add_u32 s58, s58, 0x180000
	s_addc_u32 s59, s59, 0
	s_add_u32 s50, s50, 0x180000
	s_waitcnt vmcnt(0) lgkmcnt(0)
	s_barrier
	s_addc_u32 s51, s51, 0
	v_mov_b32_e32 v4, v8
	v_add_f32_e32 v251, v17, v198
	s_cmp_lt_u32 s90, s89
	v_permlane32_swap_b32_e32 v8, v4
	v_max_f32_e32 v178, v8, v4
	s_cbranch_scc0 .LBB0_285

; #define SB() __builtin_amdgcn_sched_barrier(0)
; #define MF32(a,b,c) __builtin_amdgcn_mfma_f32_32x32x16_bf16(a,b,c,0,0,0)
; #define EXP1(x) x=__builtin_amdgcn_exp2f((x)-mh_)
; __device__ __forceinline__ bf16x8 vfrag(lds_cptr vp,int i){ const s16x4 lo=vtr(vp+(i&3)*4096+(i>>2)*1024), hh=vtr(vp+(i&3)*4096+(i>>2)*1024+512); return (bf16x8){lo[0],lo[1],lo[2],lo[3],hh[0],hh[1],hh[2],hh[3]}; }
; __device__ __forceinline__ u32x4 packw(const f32x16&p,int base){ u32x4 w; w[0]=cvtpk_s(p[base],p[base+1]); w[1]=cvtpk_s(p[base+2],p[base+3]); w[2]=cvtpk_s(p[base+4],p[base+5]); w[3]=cvtpk_s(p[base+6],p[base+7]); return w; }
;   #define KF(i) LDSQ(kpn+((i)>>1)*2048+((i)&1)*512)
;   #define QF(d0) LDSQ(qp+(d0)*1024)
; template<int THRL,bool FIRST> __device__ __forceinline__ void step_main(f32x16&p0,f32x16&p1,f32x16&n0,f32x16&n1,St&S,lds_cptr kpn,lds_cptr qp,lds_cptr vp,float*wsf,int r32,int hi,float&rm){
;     ...
;   bf16x8 ka=KF(0),kb=KF(1),kc=KF(2),kd=KF(3),qa=QF(0),qb=QF(1);
;   decide<THRL,FIRST>(rm,S,wsf,r32,hi);
;   u32x4 pw0,pw1,pw2,pw3; const float mh_=S.mhat; const f32x16 z=f32x16{};
;   SB();
;   n0=MF32(ka,qa,z); ka=KF(4); EXP1(p0[0]);EXP1(p0[1]);EXP1(p0[2]); SB();
;   n1=MF32(kb,qa,z); kb=KF(5); qa=QF(2); EXP1(p0[3]);EXP1(p0[4]);EXP1(p0[5]); SB();
;   n0=MF32(kc,qb,n0);   kc=KF(6); EXP1(p0[6]);EXP1(p0[7]);EXP1(p0[8]); SB();
;   n1=MF32(kd,qb,n1);   kd=KF(7); qb=QF(3); EXP1(p0[9]);EXP1(p0[10]);EXP1(p0[11]); SB();
;   bf16x8 vfa=vfrag(vp,0);
;   n0=MF32(ka,qa,n0);   EXP1(p0[12]);EXP1(p0[13]);EXP1(p0[14]); pw0=packw(p0,0); SB();
;   bf16x8 vfb=vfrag(vp,1);
;   n1=MF32(kb,qa,n1);   EXP1(p0[15]);EXP1(p1[0]);EXP1(p1[1]); SB();
;   bf16x8 vfc=vfrag(vp,2);
;   n0=MF32(kc,qb,n0);   EXP1(p1[2]);EXP1(p1[3]);EXP1(p1[4]); pw1=packw(p0,8); SB();
;   bf16x8 vfd=vfrag(vp,3);
;   n1=MF32(kd,qb,n1);   EXP1(p1[5]);EXP1(p1[6]);EXP1(p1[7]); SB();
;     ...
;   float sa=p0[0]+p0[1];
;     ...
;   PVG(0,pw0,vfa,4, p0[2],p0[3],p0[4],p0[5],   do{EXP1(p1[8]);EXP1(p1[9]);}while(0));
;   PVG(1,pw0,vfb,5, p0[6],p0[7],p0[8],p0[9], do{EXP1(p1[10]);EXP1(p1[11]);}while(0));
;   PVG(2,pw0,vfc,6, p0[10],p0[11],p0[12],p0[13], do{EXP1(p1[12]);EXP1(p1[13]);}while(0));
;   PVG(3,pw0,vfd,7, p0[14],p0[15],p1[0],p1[1],   do{EXP1(p1[14]);EXP1(p1[15]);}while(0));
.LBB0_282:
	s_add_i32 s4, s88, 0x2000
	s_cmpk_lg_i32 s88, 0x4000
	s_cselect_b32 s91, s4, 0
	v_mfma_f32_32x32x16_bf16 v[130:145], v[204:207], v[164:167], v[146:161]
	s_add_i32 s4, s91, s84
	s_mov_b32 s5, m0
	s_mov_b32 m0, s4
	s_nop 0
	global_load_lds_dwordx4 v252, s[58:59]
	s_mov_b32 m0, s5
	v_exp_f32_e32 v190, v98
	v_exp_f32_e32 v191, v99
	v_exp_f32_e32 v192, v100
	v_mfma_f32_32x32x16_bf16 v[114:129], v[208:211], v[164:167], v[146:161]
	v_exp_f32_e32 v193, v101
	v_exp_f32_e32 v194, v102
	v_exp_f32_e32 v195, v103
	v_mfma_f32_32x32x16_bf16 v[130:145], v[212:215], v[168:171], v[130:145]
	v_exp_f32_e32 v196, v104
	v_exp_f32_e32 v197, v105
	v_exp_f32_e32 v198, v106
	v_mfma_f32_32x32x16_bf16 v[114:129], v[216:219], v[168:171], v[114:129]
	v_exp_f32_e32 v17, v107
	v_exp_f32_e32 v199, v108
	v_exp_f32_e32 v200, v109
	v_mfma_f32_32x32x16_bf16 v[130:145], v[220:223], v[172:175], v[130:145]
	s_mov_b32 s4, m0
	s_mov_b32 m0, s79
	s_nop 0
	global_load_lds_dwordx4 v250, s[50:51]
	s_mov_b32 m0, s4
	v_exp_f32_e32 v201, v110
	ds_read_b64_tr_b16 v[4:5], v246 offset:24576
	ds_read_b64_tr_b16 v[6:7], v246 offset:25088
	v_exp_f32_e32 v202, v111
	v_exp_f32_e32 v178, v112
	v_cvt_pk_bf16_f32 v8, v190, v191
	v_cvt_pk_bf16_f32 v9, v192, v193
	v_cvt_pk_bf16_f32 v10, v194, v195
	v_cvt_pk_bf16_f32 v11, v196, v197
	v_mfma_f32_32x32x16_bf16 v[114:129], v[224:227], v[172:175], v[114:129]
	ds_read_b64_tr_b16 v[106:107], v246 offset:28672
	ds_read_b64_tr_b16 v[108:109], v246 offset:29184
	v_exp_f32_e32 v180, v82
	v_exp_f32_e32 v179, v113
	v_exp_f32_e32 v181, v83
	v_mfma_f32_32x32x16_bf16 v[130:145], v[228:231], v[236:239], v[130:145]
	ds_read_b64_tr_b16 v[110:111], v246 offset:32768
	ds_read_b64_tr_b16 v[112:113], v246 offset:33280
	v_exp_f32_e32 v182, v84
	v_exp_f32_e32 v183, v85
	v_exp_f32_e32 v184, v86
	v_cvt_pk_bf16_f32 v82, v198, v17
	v_cvt_pk_bf16_f32 v83, v199, v200
	v_cvt_pk_bf16_f32 v84, v201, v202
	v_cvt_pk_bf16_f32 v85, v178, v179
	v_mfma_f32_32x32x16_bf16 v[114:129], v[232:235], v[236:239], v[114:129]
	v_add_u32_e32 v240, s88, v249
	ds_read_b64_tr_b16 v[98:99], v246 offset:36864
	ds_read_b64_tr_b16 v[100:101], v246 offset:37376
	v_exp_f32_e32 v185, v87
	v_exp_f32_e32 v186, v88
	v_exp_f32_e32 v187, v89
	s_waitcnt lgkmcnt(6)
	v_mfma_f32_32x32x16_bf16 v[18:33], v[8:11], v[4:7], v[18:33]
	ds_read_b128 v[204:207], v240
	s_add_u32 s60, s50, 0x80
	s_addc_u32 s61, s51, 0
	s_mov_b32 s4, m0
	s_mov_b32 m0, s41
	s_nop 0
	global_load_lds_dwordx4 v250, s[60:61]
	s_mov_b32 m0, s4
	v_add_f32_e32 v86, v190, v191
	ds_read_b64_tr_b16 v[12:13], v246 offset:25600
	ds_read_b64_tr_b16 v[14:15], v246 offset:26112
	v_add_f32_e32 v86, v192, v86
	v_exp_f32_e32 v103, v91
	v_add_f32_e32 v4, v193, v86
	v_add_f32_e32 v4, v194, v4
	v_add_f32_e32 v86, v195, v4
	v_exp_f32_e32 v102, v90
	s_waitcnt lgkmcnt(7)
	v_mfma_f32_32x32x16_bf16 v[34:49], v[8:11], v[106:109], v[34:49]
	ds_read_b64_tr_b16 v[4:5], v246 offset:29696
	ds_read_b64_tr_b16 v[6:7], v246 offset:30208
	ds_read_b128 v[208:211], v240 offset:512
	v_add_f32_e32 v86, v196, v86
	v_add_f32_e32 v86, v197, v86
	v_add_f32_e32 v86, v198, v86
	v_exp_f32_e32 v104, v92
	v_add_f32_e32 v17, v17, v86
	v_exp_f32_e32 v105, v93
	s_waitcnt lgkmcnt(8)
	v_mfma_f32_32x32x16_bf16 v[50:65], v[8:11], v[110:113], v[50:65]
	ds_read_b64_tr_b16 v[86:87], v246 offset:33792
	ds_read_b64_tr_b16 v[88:89], v246 offset:34304
	ds_read_b128 v[212:215], v240 offset:2048
	v_add_f32_e32 v17, v199, v17
	v_add_f32_e32 v17, v200, v17
	v_add_f32_e32 v17, v201, v17
	v_exp_f32_e32 v106, v94
	v_add_f32_e32 v17, v202, v17
	v_exp_f32_e32 v107, v95
	s_waitcnt lgkmcnt(9)
	v_mfma_f32_32x32x16_bf16 v[66:81], v[8:11], v[98:101], v[66:81]
	ds_read_b64_tr_b16 v[90:91], v246 offset:37888
	ds_read_b64_tr_b16 v[92:93], v246 offset:38400
	ds_read_b128 v[216:219], v240 offset:2560
	v_add_f32_e32 v17, v178, v17
	v_add_f32_e32 v8, v179, v17
	v_add_f32_e32 v8, v180, v8
	v_exp_f32_e32 v108, v96
	v_add_f32_e32 v17, v181, v8
	v_exp_f32_e32 v109, v97
	s_waitcnt lgkmcnt(9)
; __device__ __forceinline__ float max2f(float a,float b){float r;asm("v_max_f32_e32 %0, %1, %2":"=v"(r):"v"(a),"v"(b));return r;}
; template<int THRL,bool FIRST> __device__ __forceinline__ void decide(float rm,St&S,float*wsf,int r32,int hi){
;     ...
;   else if(__any(rm-S.mhat>(float)THRL)){
;     const float dl=__builtin_fmaxf(rm-S.mhat,0.f); S.mhat+=dl;
;     const float f=__builtin_amdgcn_exp2f(-dl); S.l_reg*=f; if(hi==0)wsf[r32]=f;
;     asm volatile("s_waitcnt lgkmcnt(0)":::"memory");
; template<int THRL,bool FIRST> __device__ __forceinline__ void step_main(f32x16&p0,f32x16&p1,f32x16&n0,f32x16&n1,St&S,lds_cptr kpn,lds_cptr qp,lds_cptr vp,float*wsf,int r32,int hi,float&rm){
;     ...
;   PVG(0,pw0,vfa,4, p0[2],p0[3],p0[4],p0[5],   do{EXP1(p1[8]);EXP1(p1[9]);}while(0));
;   PVG(1,pw0,vfb,5, p0[6],p0[7],p0[8],p0[9], do{EXP1(p1[10]);EXP1(p1[11]);}while(0));
;   PVG(2,pw0,vfc,6, p0[10],p0[11],p0[12],p0[13], do{EXP1(p1[12]);EXP1(p1[13]);}while(0));
;   PVG(3,pw0,vfd,7, p0[14],p0[15],p1[0],p1[1],   do{EXP1(p1[14]);EXP1(p1[15]);}while(0));
;   PVG(4,pw1,vfa,8, p1[2],p1[3],p1[4],p1[5],   pw2=packw(p1,0));
;   PVG(5,pw1,vfb,9, p1[6],p1[7],p1[8],p1[9], pw3=packw(p1,8));
;   PVG(6,pw1,vfc,10, p1[10],p1[11],p1[12],p1[13], do{}while(0));
;   PVG(7,pw1,vfd,11, p1[14],p1[15],0.f,0.f, do{}while(0));
;   float ma,mb;
;     ...
;   PVG(8,pw2,vfa,12,0.f,0.f,0.f,0.f, do{ma=max3f(n0[0],n0[1],n1[0]);mb=max3f(n0[2],n0[3],n1[1]);PINAB();}while(0));
;   PVG(9,pw2,vfb,13,0.f,0.f,0.f,0.f, do{ma=max3f(ma,n1[2],n1[3]);mb=max3f(mb,n0[4],n0[5]);PINAB();}while(0));
;   PVG(10,pw2,vfc,14,0.f,0.f,0.f,0.f, do{ma=max3f(ma,n0[6],n0[7]);mb=max3f(mb,n1[4],n1[5]);PINAB();}while(0));
;   PVG(11,pw2,vfd,15,0.f,0.f,0.f,0.f, do{ma=max3f(ma,n1[6],n1[7]);mb=max3f(mb,n0[8],n0[9]);PINAB();}while(0));
;   PVG(12,pw3,vfa,16,0.f,0.f,0.f,0.f, do{ma=max3f(ma,n0[10],n0[11]);mb=max3f(mb,n1[8],n1[9]);PINAB();}while(0));
;   PVG(13,pw3,vfb,16,0.f,0.f,0.f,0.f, do{ma=max3f(ma,n1[10],n1[11]);mb=max3f(mb,n0[12],n0[13]);PINAB();}while(0));
;   PVG(14,pw3,vfc,16,0.f,0.f,0.f,0.f, do{ma=max3f(ma,n0[14],n0[15]);mb=max3f(mb,n1[12],n1[13]);PINAB();}while(0));
;   PVG(15,pw3,vfd,16,0.f,0.f,0.f,0.f, do{ma=max3f(ma,n1[14],n1[15]);ma=max2f(ma,mb);PINAB();}while(0));
;     ...
;   { auto rr=__builtin_amdgcn_permlane32_swap(__float_as_uint(ma),__float_as_uint(ma),false,false); rm=max2f(__uint_as_float(rr[0]),__uint_as_float(rr[1])); }
;     ...
;   S.l_reg+=sa;
	v_mfma_f32_32x32x16_bf16 v[18:33], v[82:85], v[12:15], v[18:33]
	ds_read_b64_tr_b16 v[8:9], v246 offset:26624
	ds_read_b64_tr_b16 v[10:11], v246 offset:27136
	ds_read_b128 v[220:223], v240 offset:4096
	v_add_f32_e32 v17, v182, v17
	v_add_f32_e32 v17, v183, v17
	v_add_f32_e32 v17, v184, v17
	v_add_f32_e32 v17, v185, v17
	v_cvt_pk_bf16_f32 v12, v180, v181
	v_cvt_pk_bf16_f32 v13, v182, v183
	v_cvt_pk_bf16_f32 v14, v184, v185
	v_cvt_pk_bf16_f32 v15, v186, v187
	s_waitcnt lgkmcnt(10)
	v_mfma_f32_32x32x16_bf16 v[34:49], v[82:85], v[4:7], v[34:49]
	ds_read_b64_tr_b16 v[94:95], v246 offset:30720
	ds_read_b64_tr_b16 v[96:97], v246 offset:31232
	ds_read_b128 v[224:227], v240 offset:4608
	v_add_f32_e32 v17, v186, v17
	v_add_f32_e32 v17, v187, v17
	v_add_f32_e32 v17, v102, v17
	v_add_f32_e32 v17, v103, v17
	v_cvt_pk_bf16_f32 v4, v102, v103
	v_cvt_pk_bf16_f32 v5, v104, v105
	v_cvt_pk_bf16_f32 v6, v106, v107
	v_cvt_pk_bf16_f32 v7, v108, v109
	s_waitcnt lgkmcnt(10)
	v_mfma_f32_32x32x16_bf16 v[50:65], v[82:85], v[86:89], v[50:65]
	ds_read_b64_tr_b16 v[98:99], v246 offset:34816
	ds_read_b64_tr_b16 v[100:101], v246 offset:35328
	ds_read_b128 v[228:231], v240 offset:6144
	v_add_f32_e32 v17, v104, v17
	v_add_f32_e32 v17, v105, v17
	v_add_f32_e32 v17, v106, v17
	v_add_f32_e32 v17, v107, v17
	s_waitcnt lgkmcnt(10)
	v_mfma_f32_32x32x16_bf16 v[66:81], v[82:85], v[90:93], v[66:81]
	ds_read_b64_tr_b16 v[86:87], v246 offset:38912
	ds_read_b64_tr_b16 v[88:89], v246 offset:39424
	ds_read_b128 v[232:235], v240 offset:6656
	v_add_f32_e32 v17, v108, v17
	v_add_f32_e32 v17, v109, v17
	v_add_f32_e32 v17, 0, v17
	s_waitcnt lgkmcnt(10)
	v_mfma_f32_32x32x16_bf16 v[18:33], v[12:15], v[8:11], v[18:33]
	ds_read_b64_tr_b16 v[82:83], v246 offset:27648
	ds_read_b64_tr_b16 v[84:85], v246 offset:28160
	v_max3_f32 v90, v130, v131, v114
	v_max3_f32 v91, v132, v133, v115
	s_nop 0
	s_waitcnt lgkmcnt(9)
	v_mfma_f32_32x32x16_bf16 v[34:49], v[12:15], v[94:97], v[34:49]
	ds_read_b64_tr_b16 v[8:9], v246 offset:31744
	ds_read_b64_tr_b16 v[10:11], v246 offset:32256
	v_max3_f32 v102, v90, v116, v117
	v_max3_f32 v103, v91, v134, v135
	s_nop 0
	s_waitcnt lgkmcnt(8)
	v_mfma_f32_32x32x16_bf16 v[50:65], v[12:15], v[98:101], v[50:65]
	ds_read_b64_tr_b16 v[90:91], v246 offset:35840
	ds_read_b64_tr_b16 v[92:93], v246 offset:36352
	v_max3_f32 v102, v102, v136, v137
	v_max3_f32 v103, v103, v118, v119
	s_nop 0
	s_waitcnt lgkmcnt(7)
	v_mfma_f32_32x32x16_bf16 v[66:81], v[12:15], v[86:89], v[66:81]
	ds_read_b64_tr_b16 v[94:95], v246 offset:39936
	ds_read_b64_tr_b16 v[96:97], v246 offset:40448
	v_max3_f32 v98, v102, v120, v121
	v_max3_f32 v99, v103, v138, v139
	s_nop 0
	s_waitcnt lgkmcnt(6)
	v_mfma_f32_32x32x16_bf16 v[18:33], v[4:7], v[82:85], v[18:33]
	v_max3_f32 v12, v98, v140, v141
	v_max3_f32 v13, v99, v122, v123
	s_nop 0
	s_waitcnt lgkmcnt(4)
	v_mfma_f32_32x32x16_bf16 v[34:49], v[4:7], v[8:11], v[34:49]
	v_max3_f32 v12, v12, v124, v125
	v_max3_f32 v13, v13, v142, v143
	s_nop 0
	s_waitcnt lgkmcnt(2)
	v_mfma_f32_32x32x16_bf16 v[50:65], v[4:7], v[90:93], v[50:65]
	v_max3_f32 v8, v12, v144, v145
	v_max3_f32 v9, v13, v126, v127
	s_nop 0
	s_waitcnt lgkmcnt(0)
	v_mfma_f32_32x32x16_bf16 v[66:81], v[4:7], v[94:97], v[66:81]
	v_max3_f32 v8, v8, v128, v129
	s_nop 0
	v_max_f32_e32 v8, v8, v9
	s_nop 0
	v_mov_b32_e32 v162, v8
	v_mov_b32_e32 v163, v8
	s_waitcnt vmcnt(0) lgkmcnt(0)
	s_barrier
	v_permlane32_swap_b32_e32 v162, v163
	v_max_f32_e32 v94, v162, v163
	v_add_f32_e32 v17, v251, v17
	v_cmp_lt_f32_e32 vcc, s69, v94
	s_cbranch_vccz .LBB0_277
	v_max_f32_e32 v94, v94, v94
	v_max_f32_e32 v94, 0, v94
	v_exp_f32_e64 v95, -v94
	s_and_saveexec_b64 s[60:61], s[6:7]
	s_cbranch_execz .LBB0_276
	ds_write_b32 v16, v95
	s_branch .LBB0_276

; #define SB() __builtin_amdgcn_sched_barrier(0)
; #define MF32(a,b,c) __builtin_amdgcn_mfma_f32_32x32x16_bf16(a,b,c,0,0,0)
; #define EXP1(x) x=__builtin_amdgcn_exp2f((x)-mh_)
; __device__ __forceinline__ bf16x8 vfrag(lds_cptr vp,int i){ const s16x4 lo=vtr(vp+(i&3)*4096+(i>>2)*1024), hh=vtr(vp+(i&3)*4096+(i>>2)*1024+512); return (bf16x8){lo[0],lo[1],lo[2],lo[3],hh[0],hh[1],hh[2],hh[3]}; }
; __device__ __forceinline__ u32x4 packw(const f32x16&p,int base){ u32x4 w; w[0]=cvtpk_s(p[base],p[base+1]); w[1]=cvtpk_s(p[base+2],p[base+3]); w[2]=cvtpk_s(p[base+4],p[base+5]); w[3]=cvtpk_s(p[base+6],p[base+7]); return w; }
;   #define KF(i) LDSQ(kpn+((i)>>1)*2048+((i)&1)*512)
;   #define QF(d0) LDSQ(qp+(d0)*1024)
; template<int THRL,bool FIRST> __device__ __forceinline__ void step_main(f32x16&p0,f32x16&p1,f32x16&n0,f32x16&n1,St&S,lds_cptr kpn,lds_cptr qp,lds_cptr vp,float*wsf,int r32,int hi,float&rm){
;     ...
;   bf16x8 ka=KF(0),kb=KF(1),kc=KF(2),kd=KF(3),qa=QF(0),qb=QF(1);
;   decide<THRL,FIRST>(rm,S,wsf,r32,hi);
;   u32x4 pw0,pw1,pw2,pw3; const float mh_=S.mhat; const f32x16 z=f32x16{};
;   SB();
;   n0=MF32(ka,qa,z); ka=KF(4); EXP1(p0[0]);EXP1(p0[1]);EXP1(p0[2]); SB();
;   n1=MF32(kb,qa,z); kb=KF(5); qa=QF(2); EXP1(p0[3]);EXP1(p0[4]);EXP1(p0[5]); SB();
;   n0=MF32(kc,qb,n0);   kc=KF(6); EXP1(p0[6]);EXP1(p0[7]);EXP1(p0[8]); SB();
;   n1=MF32(kd,qb,n1);   kd=KF(7); qb=QF(3); EXP1(p0[9]);EXP1(p0[10]);EXP1(p0[11]); SB();
;   bf16x8 vfa=vfrag(vp,0);
;   n0=MF32(ka,qa,n0);   EXP1(p0[12]);EXP1(p0[13]);EXP1(p0[14]); pw0=packw(p0,0); SB();
;   bf16x8 vfb=vfrag(vp,1);
;   n1=MF32(kb,qa,n1);   EXP1(p0[15]);EXP1(p1[0]);EXP1(p1[1]); SB();
;   bf16x8 vfc=vfrag(vp,2);
;   n0=MF32(kc,qb,n0);   EXP1(p1[2]);EXP1(p1[3]);EXP1(p1[4]); pw1=packw(p0,8); SB();
;   bf16x8 vfd=vfrag(vp,3);
;   n1=MF32(kd,qb,n1);   EXP1(p1[5]);EXP1(p1[6]);EXP1(p1[7]); SB();
;     ...
;   float sa=p0[0]+p0[1];
;     ...
;   PVG(0,pw0,vfa,4, p0[2],p0[3],p0[4],p0[5],   do{EXP1(p1[8]);EXP1(p1[9]);}while(0));
;   PVG(1,pw0,vfb,5, p0[6],p0[7],p0[8],p0[9], do{EXP1(p1[10]);EXP1(p1[11]);}while(0));
;   PVG(2,pw0,vfc,6, p0[10],p0[11],p0[12],p0[13], do{EXP1(p1[12]);EXP1(p1[13]);}while(0));
;   PVG(3,pw0,vfd,7, p0[14],p0[15],p1[0],p1[1],   do{EXP1(p1[14]);EXP1(p1[15]);}while(0));
.LBB0_435:
	s_add_i32 s4, s89, 0x2000
	s_cmpk_lg_i32 s89, 0x4000
	s_cselect_b32 s86, s4, 0
	s_add_i32 s88, s88, 2
	v_mfma_f32_32x32x16_bf16 v[98:113], v[204:207], v[164:167], v[146:161]
	s_add_i32 s4, s86, s80
	s_add_u32 s58, s50, 0xc0000
	s_addc_u32 s59, s51, 0
	s_mov_b32 s5, m0
	s_mov_b32 m0, s4
	s_nop 0
	global_load_lds_dwordx4 v252, s[58:59]
	s_mov_b32 m0, s5
	v_exp_f32_e32 v130, v130
	v_exp_f32_e32 v131, v131
	v_exp_f32_e32 v132, v132
	v_exp_f32_e32 v133, v133
	v_exp_f32_e32 v134, v134
	v_exp_f32_e32 v135, v135
	v_mfma_f32_32x32x16_bf16 v[82:97], v[208:211], v[164:167], v[146:161]
	v_mfma_f32_32x32x16_bf16 v[98:113], v[212:215], v[168:171], v[98:113]
	v_exp_f32_e32 v136, v136
	v_exp_f32_e32 v137, v137
	v_exp_f32_e32 v138, v138
	v_mfma_f32_32x32x16_bf16 v[82:97], v[216:219], v[168:171], v[82:97]
	v_exp_f32_e32 v139, v139
	v_exp_f32_e32 v140, v140
	v_exp_f32_e32 v141, v141
	v_mfma_f32_32x32x16_bf16 v[98:113], v[220:223], v[172:175], v[98:113]
	s_add_u32 s58, s48, 0xc0000
	s_addc_u32 s59, s49, 0
	s_mov_b32 s4, m0
	s_mov_b32 m0, s78
	s_nop 0
	global_load_lds_dwordx4 v250, s[58:59]
	s_mov_b32 m0, s4
	v_exp_f32_e32 v142, v142
	ds_read_b64_tr_b16 v[4:5], v246 offset:40960
	ds_read_b64_tr_b16 v[6:7], v246 offset:41472
	v_exp_f32_e32 v143, v143
	v_exp_f32_e32 v144, v144
	v_cvt_pk_bf16_f32 v8, v130, v131
	v_cvt_pk_bf16_f32 v9, v132, v133
	v_cvt_pk_bf16_f32 v10, v134, v135
	v_cvt_pk_bf16_f32 v11, v136, v137
	v_mfma_f32_32x32x16_bf16 v[82:97], v[224:227], v[172:175], v[82:97]
	ds_read_b64_tr_b16 v[178:179], v246 offset:45056
	ds_read_b64_tr_b16 v[180:181], v246 offset:45568
	v_exp_f32_e32 v145, v145
	v_exp_f32_e32 v114, v114
	v_exp_f32_e32 v115, v115
	v_mfma_f32_32x32x16_bf16 v[98:113], v[228:231], v[236:239], v[98:113]
	ds_read_b64_tr_b16 v[182:183], v246 offset:49152
	ds_read_b64_tr_b16 v[184:185], v246 offset:49664
	v_exp_f32_e32 v116, v116
	v_exp_f32_e32 v117, v117
	v_exp_f32_e32 v118, v118
	v_cvt_pk_bf16_f32 v186, v138, v139
	v_cvt_pk_bf16_f32 v187, v140, v141
	v_cvt_pk_bf16_f32 v188, v142, v143
	v_cvt_pk_bf16_f32 v189, v144, v145
	v_mfma_f32_32x32x16_bf16 v[82:97], v[232:235], v[236:239], v[82:97]
	v_add_u32_e32 v240, s89, v249
	ds_read_b64_tr_b16 v[190:191], v246 offset:53248
	ds_read_b64_tr_b16 v[192:193], v246 offset:53760
	v_exp_f32_e32 v119, v119
	v_exp_f32_e32 v120, v120
	v_exp_f32_e32 v121, v121
	s_waitcnt lgkmcnt(6)
	v_mfma_f32_32x32x16_bf16 v[18:33], v[8:11], v[4:7], v[18:33]
	ds_read_b64_tr_b16 v[12:13], v246 offset:41984
	ds_read_b64_tr_b16 v[14:15], v246 offset:42496
	ds_read_b128 v[204:207], v240
	s_add_u32 s58, s48, 0xc0080
	s_addc_u32 s59, s49, 0
	s_mov_b32 s4, m0
	s_mov_b32 m0, s79
	s_nop 0
	global_load_lds_dwordx4 v250, s[58:59]
	s_mov_b32 m0, s4
	v_add_f32_e32 v194, v130, v131
	v_exp_f32_e32 v122, v122
	v_exp_f32_e32 v123, v123
	v_add_f32_e32 v194, v132, v194
	v_add_f32_e32 v4, v133, v194
	v_add_f32_e32 v4, v134, v4
	v_add_f32_e32 v194, v135, v4
	s_waitcnt lgkmcnt(7)
	v_mfma_f32_32x32x16_bf16 v[34:49], v[8:11], v[178:181], v[34:49]
	ds_read_b64_tr_b16 v[4:5], v246 offset:46080
	ds_read_b64_tr_b16 v[6:7], v246 offset:46592
	ds_read_b128 v[208:211], v240 offset:512
	v_exp_f32_e32 v124, v124
	v_exp_f32_e32 v125, v125
	v_add_f32_e32 v194, v136, v194
	v_add_f32_e32 v178, v137, v194
	v_add_f32_e32 v178, v138, v178
	v_add_f32_e32 v194, v139, v178
	s_waitcnt lgkmcnt(8)
	v_mfma_f32_32x32x16_bf16 v[50:65], v[8:11], v[182:185], v[50:65]
	ds_read_b64_tr_b16 v[178:179], v246 offset:50176
	ds_read_b64_tr_b16 v[180:181], v246 offset:50688
	ds_read_b128 v[212:215], v240 offset:2048
	v_exp_f32_e32 v126, v126
	v_exp_f32_e32 v127, v127
	v_add_f32_e32 v194, v140, v194
	v_add_f32_e32 v182, v141, v194
	v_add_f32_e32 v182, v142, v182
	v_add_f32_e32 v194, v143, v182
	s_waitcnt lgkmcnt(9)
; #define EXP1(x) x=__builtin_amdgcn_exp2f((x)-mh_)
; template<int THRL,bool FIRST> __device__ __forceinline__ void step_main(f32x16&p0,f32x16&p1,f32x16&n0,f32x16&n1,St&S,lds_cptr kpn,lds_cptr qp,lds_cptr vp,float*wsf,int r32,int hi,float&rm){
;     ...
;   PVG(0,pw0,vfa,4, p0[2],p0[3],p0[4],p0[5],   do{EXP1(p1[8]);EXP1(p1[9]);}while(0));
;   PVG(1,pw0,vfb,5, p0[6],p0[7],p0[8],p0[9], do{EXP1(p1[10]);EXP1(p1[11]);}while(0));
;   PVG(2,pw0,vfc,6, p0[10],p0[11],p0[12],p0[13], do{EXP1(p1[12]);EXP1(p1[13]);}while(0));
;   PVG(3,pw0,vfd,7, p0[14],p0[15],p1[0],p1[1],   do{EXP1(p1[14]);EXP1(p1[15]);}while(0));
;   PVG(4,pw1,vfa,8, p1[2],p1[3],p1[4],p1[5],   pw2=packw(p1,0));
;   PVG(5,pw1,vfb,9, p1[6],p1[7],p1[8],p1[9], pw3=packw(p1,8));
;   PVG(6,pw1,vfc,10, p1[10],p1[11],p1[12],p1[13], do{}while(0));
;   PVG(7,pw1,vfd,11, p1[14],p1[15],0.f,0.f, do{}while(0));
;   float ma,mb;
;     ...
;   PVG(8,pw2,vfa,12,0.f,0.f,0.f,0.f, do{ma=max3f(n0[0],n0[1],n1[0]);mb=max3f(n0[2],n0[3],n1[1]);PINAB();}while(0));
;   PVG(9,pw2,vfb,13,0.f,0.f,0.f,0.f, do{ma=max3f(ma,n1[2],n1[3]);mb=max3f(mb,n0[4],n0[5]);PINAB();}while(0));
;   PVG(10,pw2,vfc,14,0.f,0.f,0.f,0.f, do{ma=max3f(ma,n0[6],n0[7]);mb=max3f(mb,n1[4],n1[5]);PINAB();}while(0));
;   PVG(11,pw2,vfd,15,0.f,0.f,0.f,0.f, do{ma=max3f(ma,n1[6],n1[7]);mb=max3f(mb,n0[8],n0[9]);PINAB();}while(0));
;   PVG(12,pw3,vfa,16,0.f,0.f,0.f,0.f, do{ma=max3f(ma,n0[10],n0[11]);mb=max3f(mb,n1[8],n1[9]);PINAB();}while(0));
;   PVG(13,pw3,vfb,16,0.f,0.f,0.f,0.f, do{ma=max3f(ma,n1[10],n1[11]);mb=max3f(mb,n0[12],n0[13]);PINAB();}while(0));
;   PVG(14,pw3,vfc,16,0.f,0.f,0.f,0.f, do{ma=max3f(ma,n0[14],n0[15]);mb=max3f(mb,n1[12],n1[13]);PINAB();}while(0));
;   PVG(15,pw3,vfd,16,0.f,0.f,0.f,0.f, do{ma=max3f(ma,n1[14],n1[15]);ma=max2f(ma,mb);PINAB();}while(0));
;     ...
;   { auto rr=__builtin_amdgcn_permlane32_swap(__float_as_uint(ma),__float_as_uint(ma),false,false); rm=max2f(__uint_as_float(rr[0]),__uint_as_float(rr[1])); }
;     ...
;   S.l_reg+=sa;
; template<int THRL> __device__ __forceinline__ void unit(int qb,const bf16*Q,const bf16*K,const bf16*V,bf16*O,char*shm){
;     ...
;     for(t=2;t<NT-4;t+=2){
;       DMA_K(t+2,ks2); DMA_V(t+1,VBUF);
;       step_main<THRL,false>(pA0,pA1,pB0,pB1,S,kp0+ks1,qp,vp0,wsf,r32,hi,rm); A128_WAITBAR(); ROT();
;       DMA_K(t+3,ks2); DMA_V(t+2,0);
;       step_main<THRL,false>(pB0,pB1,pA0,pA1,S,kp0+ks1,qp,vp0+VBUF,wsf,r32,hi,rm); A128_WAITBAR(); ROT();
;     }
	v_mfma_f32_32x32x16_bf16 v[66:81], v[8:11], v[190:193], v[66:81]
	ds_read_b64_tr_b16 v[182:183], v246 offset:54272
	ds_read_b64_tr_b16 v[184:185], v246 offset:54784
	ds_read_b128 v[216:219], v240 offset:2560
	v_exp_f32_e32 v128, v128
	v_exp_f32_e32 v129, v129
	v_add_f32_e32 v194, v144, v194
	v_add_f32_e32 v8, v145, v194
	v_add_f32_e32 v8, v114, v8
	v_add_f32_e32 v190, v115, v8
	s_waitcnt lgkmcnt(10)
	v_mfma_f32_32x32x16_bf16 v[18:33], v[186:189], v[12:15], v[18:33]
	ds_read_b64_tr_b16 v[8:9], v246 offset:43008
	ds_read_b64_tr_b16 v[10:11], v246 offset:43520
	ds_read_b128 v[220:223], v240 offset:4096
	v_add_f32_e32 v190, v116, v190
	v_add_f32_e32 v190, v117, v190
	v_add_f32_e32 v190, v118, v190
	v_add_f32_e32 v194, v119, v190
	v_cvt_pk_bf16_f32 v12, v114, v115
	v_cvt_pk_bf16_f32 v13, v116, v117
	v_cvt_pk_bf16_f32 v14, v118, v119
	v_cvt_pk_bf16_f32 v15, v120, v121
	s_waitcnt lgkmcnt(10)
	v_mfma_f32_32x32x16_bf16 v[34:49], v[186:189], v[4:7], v[34:49]
	ds_read_b64_tr_b16 v[190:191], v246 offset:47104
	ds_read_b64_tr_b16 v[192:193], v246 offset:47616
	ds_read_b128 v[224:227], v240 offset:4608
	v_add_f32_e32 v194, v120, v194
	v_add_f32_e32 v194, v121, v194
	v_add_f32_e32 v194, v122, v194
	v_add_f32_e32 v198, v123, v194
	v_cvt_pk_bf16_f32 v4, v122, v123
	v_cvt_pk_bf16_f32 v5, v124, v125
	v_cvt_pk_bf16_f32 v6, v126, v127
	v_cvt_pk_bf16_f32 v7, v128, v129
	s_waitcnt lgkmcnt(10)
	v_mfma_f32_32x32x16_bf16 v[50:65], v[186:189], v[178:181], v[50:65]
	ds_read_b64_tr_b16 v[194:195], v246 offset:51200
	ds_read_b64_tr_b16 v[196:197], v246 offset:51712
	ds_read_b128 v[228:231], v240 offset:6144
	v_add_f32_e32 v198, v124, v198
	v_add_f32_e32 v198, v125, v198
	v_add_f32_e32 v198, v126, v198
	v_add_f32_e32 v198, v127, v198
	s_waitcnt lgkmcnt(10)
	v_mfma_f32_32x32x16_bf16 v[66:81], v[186:189], v[182:185], v[66:81]
	ds_read_b64_tr_b16 v[178:179], v246 offset:55296
	ds_read_b64_tr_b16 v[180:181], v246 offset:55808
	ds_read_b128 v[232:235], v240 offset:6656
	v_add_f32_e32 v198, v128, v198
	v_add_f32_e32 v198, v129, v198
	v_add_f32_e32 v198, 0, v198
	s_waitcnt lgkmcnt(10)
	v_mfma_f32_32x32x16_bf16 v[18:33], v[12:15], v[8:11], v[18:33]
	ds_read_b64_tr_b16 v[182:183], v246 offset:44032
	ds_read_b64_tr_b16 v[184:185], v246 offset:44544
	v_max3_f32 v186, v98, v99, v82
	v_max3_f32 v187, v100, v101, v83
	s_nop 0
	s_waitcnt lgkmcnt(9)
	v_mfma_f32_32x32x16_bf16 v[34:49], v[12:15], v[190:193], v[34:49]
	ds_read_b64_tr_b16 v[8:9], v246 offset:48128
	ds_read_b64_tr_b16 v[10:11], v246 offset:48640
	v_max3_f32 v199, v186, v84, v85
	v_max3_f32 v200, v187, v102, v103
	s_nop 0
	s_waitcnt lgkmcnt(8)
	v_mfma_f32_32x32x16_bf16 v[50:65], v[12:15], v[194:197], v[50:65]
	ds_read_b64_tr_b16 v[186:187], v246 offset:52224
	ds_read_b64_tr_b16 v[188:189], v246 offset:52736
	v_max3_f32 v199, v199, v104, v105
	v_max3_f32 v200, v200, v86, v87
	s_nop 0
	s_waitcnt lgkmcnt(7)
	v_mfma_f32_32x32x16_bf16 v[66:81], v[12:15], v[178:181], v[66:81]
	ds_read_b64_tr_b16 v[190:191], v246 offset:56320
	ds_read_b64_tr_b16 v[192:193], v246 offset:56832
	v_max3_f32 v194, v199, v88, v89
	v_max3_f32 v195, v200, v106, v107
	s_nop 0
	s_waitcnt lgkmcnt(6)
	v_mfma_f32_32x32x16_bf16 v[18:33], v[4:7], v[182:185], v[18:33]
	v_max3_f32 v12, v194, v108, v109
	v_max3_f32 v13, v195, v90, v91
	s_nop 0
	s_waitcnt lgkmcnt(4)
	v_mfma_f32_32x32x16_bf16 v[34:49], v[4:7], v[8:11], v[34:49]
	v_max3_f32 v12, v12, v92, v93
	v_max3_f32 v13, v13, v110, v111
	s_nop 0
	s_waitcnt lgkmcnt(2)
	v_mfma_f32_32x32x16_bf16 v[50:65], v[4:7], v[186:189], v[50:65]
	v_max3_f32 v8, v12, v112, v113
	v_max3_f32 v9, v13, v94, v95
	s_nop 0
	s_waitcnt lgkmcnt(0)
	v_mfma_f32_32x32x16_bf16 v[66:81], v[4:7], v[190:193], v[66:81]
	v_max3_f32 v8, v8, v96, v97
	s_nop 0
	v_max_f32_e32 v8, v8, v9
	s_nop 0
	s_add_u32 s50, s50, 0x180000
	s_addc_u32 s51, s51, 0
	s_add_u32 s48, s48, 0x180000
	s_waitcnt vmcnt(0) lgkmcnt(0)
	s_barrier
	s_addc_u32 s49, s49, 0
	v_mov_b32_e32 v4, v8
	v_add_f32_e32 v251, v17, v198
	s_cmp_lt_u32 s88, s87
	v_permlane32_swap_b32_e32 v8, v4
	v_max_f32_e32 v178, v8, v4
	s_cbranch_scc0 .LBB0_443

; #define SB() __builtin_amdgcn_sched_barrier(0)
; #define MF32(a,b,c) __builtin_amdgcn_mfma_f32_32x32x16_bf16(a,b,c,0,0,0)
; #define EXP1(x) x=__builtin_amdgcn_exp2f((x)-mh_)
; __device__ __forceinline__ bf16x8 vfrag(lds_cptr vp,int i){ const s16x4 lo=vtr(vp+(i&3)*4096+(i>>2)*1024), hh=vtr(vp+(i&3)*4096+(i>>2)*1024+512); return (bf16x8){lo[0],lo[1],lo[2],lo[3],hh[0],hh[1],hh[2],hh[3]}; }
; __device__ __forceinline__ u32x4 packw(const f32x16&p,int base){ u32x4 w; w[0]=cvtpk_s(p[base],p[base+1]); w[1]=cvtpk_s(p[base+2],p[base+3]); w[2]=cvtpk_s(p[base+4],p[base+5]); w[3]=cvtpk_s(p[base+6],p[base+7]); return w; }
;   #define KF(i) LDSQ(kpn+((i)>>1)*2048+((i)&1)*512)
;   #define QF(d0) LDSQ(qp+(d0)*1024)
; template<int THRL,bool FIRST> __device__ __forceinline__ void step_main(f32x16&p0,f32x16&p1,f32x16&n0,f32x16&n1,St&S,lds_cptr kpn,lds_cptr qp,lds_cptr vp,float*wsf,int r32,int hi,float&rm){
;     ...
;   bf16x8 ka=KF(0),kb=KF(1),kc=KF(2),kd=KF(3),qa=QF(0),qb=QF(1);
;   decide<THRL,FIRST>(rm,S,wsf,r32,hi);
;   u32x4 pw0,pw1,pw2,pw3; const float mh_=S.mhat; const f32x16 z=f32x16{};
;   SB();
;   n0=MF32(ka,qa,z); ka=KF(4); EXP1(p0[0]);EXP1(p0[1]);EXP1(p0[2]); SB();
;   n1=MF32(kb,qa,z); kb=KF(5); qa=QF(2); EXP1(p0[3]);EXP1(p0[4]);EXP1(p0[5]); SB();
;   n0=MF32(kc,qb,n0);   kc=KF(6); EXP1(p0[6]);EXP1(p0[7]);EXP1(p0[8]); SB();
;   n1=MF32(kd,qb,n1);   kd=KF(7); qb=QF(3); EXP1(p0[9]);EXP1(p0[10]);EXP1(p0[11]); SB();
;   bf16x8 vfa=vfrag(vp,0);
;   n0=MF32(ka,qa,n0);   EXP1(p0[12]);EXP1(p0[13]);EXP1(p0[14]); pw0=packw(p0,0); SB();
;   bf16x8 vfb=vfrag(vp,1);
;   n1=MF32(kb,qa,n1);   EXP1(p0[15]);EXP1(p1[0]);EXP1(p1[1]); SB();
;   bf16x8 vfc=vfrag(vp,2);
;   n0=MF32(kc,qb,n0);   EXP1(p1[2]);EXP1(p1[3]);EXP1(p1[4]); pw1=packw(p0,8); SB();
;   bf16x8 vfd=vfrag(vp,3);
;   n1=MF32(kd,qb,n1);   EXP1(p1[5]);EXP1(p1[6]);EXP1(p1[7]); SB();
;     ...
;   float sa=p0[0]+p0[1];
;     ...
;   PVG(0,pw0,vfa,4, p0[2],p0[3],p0[4],p0[5],   do{EXP1(p1[8]);EXP1(p1[9]);}while(0));
;   PVG(1,pw0,vfb,5, p0[6],p0[7],p0[8],p0[9], do{EXP1(p1[10]);EXP1(p1[11]);}while(0));
;   PVG(2,pw0,vfc,6, p0[10],p0[11],p0[12],p0[13], do{EXP1(p1[12]);EXP1(p1[13]);}while(0));
;   PVG(3,pw0,vfd,7, p0[14],p0[15],p1[0],p1[1],   do{EXP1(p1[14]);EXP1(p1[15]);}while(0));
.LBB0_440:
	s_add_i32 s4, s86, 0x2000
	s_cmpk_lg_i32 s86, 0x4000
	s_cselect_b32 s89, s4, 0
	v_mfma_f32_32x32x16_bf16 v[130:145], v[204:207], v[164:167], v[146:161]
	s_add_i32 s4, s89, s80
	s_mov_b32 s5, m0
	s_mov_b32 m0, s4
	s_nop 0
	global_load_lds_dwordx4 v252, s[50:51]
	s_mov_b32 m0, s5
	v_exp_f32_e32 v190, v98
	v_exp_f32_e32 v191, v99
	v_exp_f32_e32 v192, v100
	v_mfma_f32_32x32x16_bf16 v[114:129], v[208:211], v[164:167], v[146:161]
	v_exp_f32_e32 v193, v101
	v_exp_f32_e32 v194, v102
	v_exp_f32_e32 v195, v103
	v_mfma_f32_32x32x16_bf16 v[130:145], v[212:215], v[168:171], v[130:145]
	v_exp_f32_e32 v196, v104
	v_exp_f32_e32 v197, v105
	v_exp_f32_e32 v198, v106
	v_mfma_f32_32x32x16_bf16 v[114:129], v[216:219], v[168:171], v[114:129]
	v_exp_f32_e32 v17, v107
	v_exp_f32_e32 v199, v108
	v_exp_f32_e32 v200, v109
	v_mfma_f32_32x32x16_bf16 v[130:145], v[220:223], v[172:175], v[130:145]
	s_mov_b32 s4, m0
	s_mov_b32 m0, s77
	s_nop 0
	global_load_lds_dwordx4 v250, s[48:49]
	s_mov_b32 m0, s4
	v_exp_f32_e32 v201, v110
	ds_read_b64_tr_b16 v[4:5], v246 offset:24576
	ds_read_b64_tr_b16 v[6:7], v246 offset:25088
	v_exp_f32_e32 v202, v111
	v_exp_f32_e32 v178, v112
	v_cvt_pk_bf16_f32 v8, v190, v191
	v_cvt_pk_bf16_f32 v9, v192, v193
	v_cvt_pk_bf16_f32 v10, v194, v195
	v_cvt_pk_bf16_f32 v11, v196, v197
	v_mfma_f32_32x32x16_bf16 v[114:129], v[224:227], v[172:175], v[114:129]
	ds_read_b64_tr_b16 v[106:107], v246 offset:28672
	ds_read_b64_tr_b16 v[108:109], v246 offset:29184
	v_exp_f32_e32 v180, v82
	v_exp_f32_e32 v179, v113
	v_exp_f32_e32 v181, v83
	v_mfma_f32_32x32x16_bf16 v[130:145], v[228:231], v[236:239], v[130:145]
	ds_read_b64_tr_b16 v[110:111], v246 offset:32768
	ds_read_b64_tr_b16 v[112:113], v246 offset:33280
	v_exp_f32_e32 v182, v84
	v_exp_f32_e32 v183, v85
	v_exp_f32_e32 v184, v86
	v_cvt_pk_bf16_f32 v82, v198, v17
	v_cvt_pk_bf16_f32 v83, v199, v200
	v_cvt_pk_bf16_f32 v84, v201, v202
	v_cvt_pk_bf16_f32 v85, v178, v179
	v_mfma_f32_32x32x16_bf16 v[114:129], v[232:235], v[236:239], v[114:129]
	v_add_u32_e32 v240, s86, v249
	ds_read_b64_tr_b16 v[98:99], v246 offset:36864
	ds_read_b64_tr_b16 v[100:101], v246 offset:37376
	v_exp_f32_e32 v185, v87
	v_exp_f32_e32 v186, v88
	v_exp_f32_e32 v187, v89
	s_waitcnt lgkmcnt(6)
	v_mfma_f32_32x32x16_bf16 v[18:33], v[8:11], v[4:7], v[18:33]
	ds_read_b128 v[204:207], v240
	s_add_u32 s58, s48, 0x80
	s_addc_u32 s59, s49, 0
	s_mov_b32 s4, m0
	s_mov_b32 m0, s39
	s_nop 0
	global_load_lds_dwordx4 v250, s[58:59]
	s_mov_b32 m0, s4
	v_add_f32_e32 v86, v190, v191
	ds_read_b64_tr_b16 v[12:13], v246 offset:25600
	ds_read_b64_tr_b16 v[14:15], v246 offset:26112
	v_add_f32_e32 v86, v192, v86
	v_exp_f32_e32 v103, v91
	v_add_f32_e32 v4, v193, v86
	v_add_f32_e32 v4, v194, v4
	v_add_f32_e32 v86, v195, v4
	v_exp_f32_e32 v102, v90
	s_waitcnt lgkmcnt(7)
	v_mfma_f32_32x32x16_bf16 v[34:49], v[8:11], v[106:109], v[34:49]
	ds_read_b64_tr_b16 v[4:5], v246 offset:29696
	ds_read_b64_tr_b16 v[6:7], v246 offset:30208
	ds_read_b128 v[208:211], v240 offset:512
	v_add_f32_e32 v86, v196, v86
	v_add_f32_e32 v86, v197, v86
	v_add_f32_e32 v86, v198, v86
	v_exp_f32_e32 v104, v92
	v_add_f32_e32 v17, v17, v86
	v_exp_f32_e32 v105, v93
	s_waitcnt lgkmcnt(8)
	v_mfma_f32_32x32x16_bf16 v[50:65], v[8:11], v[110:113], v[50:65]
	ds_read_b64_tr_b16 v[86:87], v246 offset:33792
	ds_read_b64_tr_b16 v[88:89], v246 offset:34304
	ds_read_b128 v[212:215], v240 offset:2048
	v_add_f32_e32 v17, v199, v17
	v_add_f32_e32 v17, v200, v17
	v_add_f32_e32 v17, v201, v17
	v_exp_f32_e32 v106, v94
	v_add_f32_e32 v17, v202, v17
	v_exp_f32_e32 v107, v95
	s_waitcnt lgkmcnt(9)
	v_mfma_f32_32x32x16_bf16 v[66:81], v[8:11], v[98:101], v[66:81]
	ds_read_b64_tr_b16 v[90:91], v246 offset:37888
	ds_read_b64_tr_b16 v[92:93], v246 offset:38400
	ds_read_b128 v[216:219], v240 offset:2560
	v_add_f32_e32 v17, v178, v17
	v_add_f32_e32 v8, v179, v17
	v_add_f32_e32 v8, v180, v8
	v_exp_f32_e32 v108, v96
	v_add_f32_e32 v17, v181, v8
	v_exp_f32_e32 v109, v97
	s_waitcnt lgkmcnt(9)
; __device__ __forceinline__ float max2f(float a,float b){float r;asm("v_max_f32_e32 %0, %1, %2":"=v"(r):"v"(a),"v"(b));return r;}
; template<int THRL,bool FIRST> __device__ __forceinline__ void decide(float rm,St&S,float*wsf,int r32,int hi){
;     ...
;   else if(__any(rm-S.mhat>(float)THRL)){
;     const float dl=__builtin_fmaxf(rm-S.mhat,0.f); S.mhat+=dl;
;     const float f=__builtin_amdgcn_exp2f(-dl); S.l_reg*=f; if(hi==0)wsf[r32]=f;
;     asm volatile("s_waitcnt lgkmcnt(0)":::"memory");
; template<int THRL,bool FIRST> __device__ __forceinline__ void step_main(f32x16&p0,f32x16&p1,f32x16&n0,f32x16&n1,St&S,lds_cptr kpn,lds_cptr qp,lds_cptr vp,float*wsf,int r32,int hi,float&rm){
;     ...
;   PVG(0,pw0,vfa,4, p0[2],p0[3],p0[4],p0[5],   do{EXP1(p1[8]);EXP1(p1[9]);}while(0));
;   PVG(1,pw0,vfb,5, p0[6],p0[7],p0[8],p0[9], do{EXP1(p1[10]);EXP1(p1[11]);}while(0));
;   PVG(2,pw0,vfc,6, p0[10],p0[11],p0[12],p0[13], do{EXP1(p1[12]);EXP1(p1[13]);}while(0));
;   PVG(3,pw0,vfd,7, p0[14],p0[15],p1[0],p1[1],   do{EXP1(p1[14]);EXP1(p1[15]);}while(0));
;   PVG(4,pw1,vfa,8, p1[2],p1[3],p1[4],p1[5],   pw2=packw(p1,0));
;   PVG(5,pw1,vfb,9, p1[6],p1[7],p1[8],p1[9], pw3=packw(p1,8));
;   PVG(6,pw1,vfc,10, p1[10],p1[11],p1[12],p1[13], do{}while(0));
;   PVG(7,pw1,vfd,11, p1[14],p1[15],0.f,0.f, do{}while(0));
;   float ma,mb;
;     ...
;   PVG(8,pw2,vfa,12,0.f,0.f,0.f,0.f, do{ma=max3f(n0[0],n0[1],n1[0]);mb=max3f(n0[2],n0[3],n1[1]);PINAB();}while(0));
;   PVG(9,pw2,vfb,13,0.f,0.f,0.f,0.f, do{ma=max3f(ma,n1[2],n1[3]);mb=max3f(mb,n0[4],n0[5]);PINAB();}while(0));
;   PVG(10,pw2,vfc,14,0.f,0.f,0.f,0.f, do{ma=max3f(ma,n0[6],n0[7]);mb=max3f(mb,n1[4],n1[5]);PINAB();}while(0));
;   PVG(11,pw2,vfd,15,0.f,0.f,0.f,0.f, do{ma=max3f(ma,n1[6],n1[7]);mb=max3f(mb,n0[8],n0[9]);PINAB();}while(0));
;   PVG(12,pw3,vfa,16,0.f,0.f,0.f,0.f, do{ma=max3f(ma,n0[10],n0[11]);mb=max3f(mb,n1[8],n1[9]);PINAB();}while(0));
;   PVG(13,pw3,vfb,16,0.f,0.f,0.f,0.f, do{ma=max3f(ma,n1[10],n1[11]);mb=max3f(mb,n0[12],n0[13]);PINAB();}while(0));
;   PVG(14,pw3,vfc,16,0.f,0.f,0.f,0.f, do{ma=max3f(ma,n0[14],n0[15]);mb=max3f(mb,n1[12],n1[13]);PINAB();}while(0));
;   PVG(15,pw3,vfd,16,0.f,0.f,0.f,0.f, do{ma=max3f(ma,n1[14],n1[15]);ma=max2f(ma,mb);PINAB();}while(0));
;     ...
;   { auto rr=__builtin_amdgcn_permlane32_swap(__float_as_uint(ma),__float_as_uint(ma),false,false); rm=max2f(__uint_as_float(rr[0]),__uint_as_float(rr[1])); }
;     ...
;   S.l_reg+=sa;
	v_mfma_f32_32x32x16_bf16 v[18:33], v[82:85], v[12:15], v[18:33]
	ds_read_b64_tr_b16 v[8:9], v246 offset:26624
	ds_read_b64_tr_b16 v[10:11], v246 offset:27136
	ds_read_b128 v[220:223], v240 offset:4096
	v_add_f32_e32 v17, v182, v17
	v_add_f32_e32 v17, v183, v17
	v_add_f32_e32 v17, v184, v17
	v_add_f32_e32 v17, v185, v17
	v_cvt_pk_bf16_f32 v12, v180, v181
	v_cvt_pk_bf16_f32 v13, v182, v183
	v_cvt_pk_bf16_f32 v14, v184, v185
	v_cvt_pk_bf16_f32 v15, v186, v187
	s_waitcnt lgkmcnt(10)
	v_mfma_f32_32x32x16_bf16 v[34:49], v[82:85], v[4:7], v[34:49]
	ds_read_b64_tr_b16 v[94:95], v246 offset:30720
	ds_read_b64_tr_b16 v[96:97], v246 offset:31232
	ds_read_b128 v[224:227], v240 offset:4608
	v_add_f32_e32 v17, v186, v17
	v_add_f32_e32 v17, v187, v17
	v_add_f32_e32 v17, v102, v17
	v_add_f32_e32 v17, v103, v17
	v_cvt_pk_bf16_f32 v4, v102, v103
	v_cvt_pk_bf16_f32 v5, v104, v105
	v_cvt_pk_bf16_f32 v6, v106, v107
	v_cvt_pk_bf16_f32 v7, v108, v109
	s_waitcnt lgkmcnt(10)
	v_mfma_f32_32x32x16_bf16 v[50:65], v[82:85], v[86:89], v[50:65]
	ds_read_b64_tr_b16 v[98:99], v246 offset:34816
	ds_read_b64_tr_b16 v[100:101], v246 offset:35328
	ds_read_b128 v[228:231], v240 offset:6144
	v_add_f32_e32 v17, v104, v17
	v_add_f32_e32 v17, v105, v17
	v_add_f32_e32 v17, v106, v17
	v_add_f32_e32 v17, v107, v17
	s_waitcnt lgkmcnt(10)
	v_mfma_f32_32x32x16_bf16 v[66:81], v[82:85], v[90:93], v[66:81]
	ds_read_b64_tr_b16 v[86:87], v246 offset:38912
	ds_read_b64_tr_b16 v[88:89], v246 offset:39424
	ds_read_b128 v[232:235], v240 offset:6656
	v_add_f32_e32 v17, v108, v17
	v_add_f32_e32 v17, v109, v17
	v_add_f32_e32 v17, 0, v17
	s_waitcnt lgkmcnt(10)
	v_mfma_f32_32x32x16_bf16 v[18:33], v[12:15], v[8:11], v[18:33]
	ds_read_b64_tr_b16 v[82:83], v246 offset:27648
	ds_read_b64_tr_b16 v[84:85], v246 offset:28160
	v_max3_f32 v90, v130, v131, v114
	v_max3_f32 v91, v132, v133, v115
	s_nop 0
	s_waitcnt lgkmcnt(9)
	v_mfma_f32_32x32x16_bf16 v[34:49], v[12:15], v[94:97], v[34:49]
	ds_read_b64_tr_b16 v[8:9], v246 offset:31744
	ds_read_b64_tr_b16 v[10:11], v246 offset:32256
	v_max3_f32 v102, v90, v116, v117
	v_max3_f32 v103, v91, v134, v135
	s_nop 0
	s_waitcnt lgkmcnt(8)
	v_mfma_f32_32x32x16_bf16 v[50:65], v[12:15], v[98:101], v[50:65]
	ds_read_b64_tr_b16 v[90:91], v246 offset:35840
	ds_read_b64_tr_b16 v[92:93], v246 offset:36352
	v_max3_f32 v102, v102, v136, v137
	v_max3_f32 v103, v103, v118, v119
	s_nop 0
	s_waitcnt lgkmcnt(7)
	v_mfma_f32_32x32x16_bf16 v[66:81], v[12:15], v[86:89], v[66:81]
	ds_read_b64_tr_b16 v[94:95], v246 offset:39936
	ds_read_b64_tr_b16 v[96:97], v246 offset:40448
	v_max3_f32 v98, v102, v120, v121
	v_max3_f32 v99, v103, v138, v139
	s_nop 0
	s_waitcnt lgkmcnt(6)
	v_mfma_f32_32x32x16_bf16 v[18:33], v[4:7], v[82:85], v[18:33]
	v_max3_f32 v12, v98, v140, v141
	v_max3_f32 v13, v99, v122, v123
	s_nop 0
	s_waitcnt lgkmcnt(4)
	v_mfma_f32_32x32x16_bf16 v[34:49], v[4:7], v[8:11], v[34:49]
	v_max3_f32 v12, v12, v124, v125
	v_max3_f32 v13, v13, v142, v143
	s_nop 0
	s_waitcnt lgkmcnt(2)
	v_mfma_f32_32x32x16_bf16 v[50:65], v[4:7], v[90:93], v[50:65]
	v_max3_f32 v8, v12, v144, v145
	v_max3_f32 v9, v13, v126, v127
	s_nop 0
	s_waitcnt lgkmcnt(0)
	v_mfma_f32_32x32x16_bf16 v[66:81], v[4:7], v[94:97], v[66:81]
	v_max3_f32 v8, v8, v128, v129
	s_nop 0
	v_max_f32_e32 v8, v8, v9
	s_nop 0
	v_mov_b32_e32 v162, v8
	v_mov_b32_e32 v163, v8
	s_waitcnt vmcnt(0) lgkmcnt(0)
	s_barrier
	v_permlane32_swap_b32_e32 v162, v163
	v_max_f32_e32 v94, v162, v163
	v_add_f32_e32 v17, v251, v17
	v_cmp_lt_f32_e32 vcc, s67, v94
	s_cbranch_vccz .LBB0_435
	v_max_f32_e32 v94, v94, v94
	v_max_f32_e32 v94, 0, v94
	v_exp_f32_e64 v95, -v94
	s_and_saveexec_b64 s[58:59], s[6:7]
	s_cbranch_execz .LBB0_434
	ds_write_b32 v16, v95
	s_branch .LBB0_434
